# every workgroup's wave 1 issues an early L2 writeback when it arrives at a grid barrier, so the XCD leader's writeback finds little dirty data; on top of the row-scale table trim
# baseline (speedup 1.0000x reference)
.LBB0_176:
	s_waitcnt vmcnt(0)
	s_waitcnt vmcnt(0)
	s_barrier
	v_readfirstlane_b32 s100, v156
	s_lshr_b32 s100, s100, 6
	s_cmp_lg_u32 s100, 1
	s_cbranch_scc1 .Lewb_0
	buffer_wbl2 sc1
.Lewb_0:
	s_mov_b64 s[26:27], exec
	v_readlane_b32 s28, v241, 4
	v_readlane_b32 s29, v241, 5
	s_and_b64 s[28:29], s[26:27], s[28:29]
	s_xor_b64 s[26:27], s[28:29], s[26:27]
	s_mov_b64 exec, s[28:29]
	s_cbranch_execz .LBB0_229
	v_readlane_b32 s19, v240, 8
	s_waitcnt vmcnt(0) expcnt(0) lgkmcnt(0)
	s_nop 0
	v_mov_b32_e32 v0, s19
	ds_read_b32 v3, v0
	v_readlane_b32 s19, v240, 9
	s_waitcnt lgkmcnt(0)
	v_cmp_ne_u32_e32 vcc, 0, v3
	v_mov_b32_e32 v0, s19
	ds_read_b32 v0, v0
	s_cbranch_vccnz .LBB0_192
	s_mov_b32 s19, 1
	s_branch .LBB0_180

.Lwin_skip:
	s_waitcnt vmcnt(0)
	s_waitcnt vmcnt(0) lgkmcnt(0)
	s_barrier
	v_readfirstlane_b32 s100, v156
	s_lshr_b32 s100, s100, 6
	s_cmp_lg_u32 s100, 1
	s_cbranch_scc1 .Lewb_1
	buffer_wbl2 sc1
.Lewb_1:
	s_mov_b64 s[0:1], exec
	v_readlane_b32 s26, v241, 4
	v_readlane_b32 s27, v241, 5
	s_and_b64 s[26:27], s[0:1], s[26:27]
	s_mov_b64 exec, s[26:27]
	s_cbranch_execz .LBB0_399
	v_readlane_b32 s2, v240, 8
	s_waitcnt vmcnt(0) expcnt(0) lgkmcnt(0)
	s_nop 0
	v_mov_b32_e32 v0, s2
	ds_read_b32 v3, v0
	v_readlane_b32 s2, v240, 9
	s_waitcnt lgkmcnt(0)
	v_cmp_ne_u32_e32 vcc, 0, v3
	v_mov_b32_e32 v0, s2
	ds_read_b32 v0, v0
	s_cbranch_vccnz .LBB0_363
	s_mov_b32 s2, 1
	s_branch .LBB0_351

.LBB0_491:
	s_waitcnt vmcnt(0)
	s_barrier
	v_readfirstlane_b32 s100, v156
	s_lshr_b32 s100, s100, 6
	s_cmp_lg_u32 s100, 1
	s_cbranch_scc1 .Lewb_2
	buffer_wbl2 sc1
.Lewb_2:
	s_mov_b64 s[0:1], exec
	v_readlane_b32 s22, v241, 4
	v_readlane_b32 s23, v241, 5
	s_and_b64 s[22:23], s[0:1], s[22:23]
	s_movk_i32 s68, 0x161
	s_mov_b64 exec, s[22:23]
	s_cbranch_execz .LBB0_543
	v_readlane_b32 s2, v240, 8
	s_waitcnt vmcnt(0) expcnt(0) lgkmcnt(0)
	s_nop 0
	v_mov_b32_e32 v0, s2
	ds_read_b32 v3, v0
	v_readlane_b32 s2, v240, 9
	s_waitcnt lgkmcnt(0)
	v_cmp_ne_u32_e32 vcc, 0, v3
	v_mov_b32_e32 v0, s2
	ds_read_b32 v0, v0
	s_cbranch_vccnz .LBB0_507
	s_mov_b32 s2, 1
	s_branch .LBB0_495

.LBB0_582:
	s_waitcnt vmcnt(0)
	s_waitcnt lgkmcnt(0)
	s_barrier
	v_readfirstlane_b32 s100, v156
	s_lshr_b32 s100, s100, 6
	s_cmp_lg_u32 s100, 1
	s_cbranch_scc1 .Lewb_3
	buffer_wbl2 sc1
.Lewb_3:
	s_mov_b64 s[0:1], exec
	v_readlane_b32 s20, v241, 4
	v_readlane_b32 s21, v241, 5
	s_and_b64 s[20:21], s[0:1], s[20:21]
	s_mov_b64 exec, s[20:21]
	s_cbranch_execz .LBB0_153
	v_readlane_b32 s2, v240, 8
	s_waitcnt vmcnt(0) expcnt(0) lgkmcnt(0)
	s_nop 0
	v_mov_b32_e32 v0, s2
	ds_read_b32 v3, v0
	v_readlane_b32 s2, v240, 9
	s_waitcnt lgkmcnt(0)
	v_cmp_ne_u32_e32 vcc, 0, v3
	v_mov_b32_e32 v0, s2
	ds_read_b32 v0, v0
	s_cbranch_vccnz .LBB0_598
	s_mov_b32 s2, 1
	s_branch .LBB0_586
